# in-projection fast epilogue also for the k / v column tiles of prompt rows (bf16 rows of pitch 512 B, f32 window rows on the last tile of a sequence)
# baseline (speedup 1.0000x reference)
.Lfi_k4_slow:
	s_cmp_lt_u32 s35, 4
	s_cbranch_scc1 .Lfi_kv
	v_readlane_b32 s2, v252, 42
	s_add_i32 s71, s71, s2
	v_add_u32_e32 v0, s71, v209
	ds_read_b128 v[150:153], v0 offset:4096
	ds_read_b128 v[146:149], v0 offset:4112
	ds_read_b128 v[142:145], v0 offset:4224
	ds_read_b128 v[138:141], v0 offset:4240
	ds_read_b128 v[0:3], v181
	s_cmp_eq_u32 s35, 2
	s_cselect_b32 s26, s85, s66
	s_cselect_b32 s27, s84, s65
	s_cselect_b32 s49, s49, s74
	s_waitcnt lgkmcnt(0)
	v_mov_b32_e32 v4, v1
	v_mov_b32_e32 v5, v2
	v_mov_b32_e32 v1, v3
	v_pk_add_f32 v[0:1], v[4:5], v[0:1]
	s_cselect_b32 s33, s37, s33
	v_add_f32_e32 v0, v0, v1
	v_fmamk_f32 v0, v0, 0x3a800000, v212
	v_mul_f32_e32 v1, 0x4b800000, v0
	v_cmp_gt_f32_e32 vcc, s59, v0
	s_lshl_b32 s36, s36, 8
	s_add_i32 s16, s36, s20
	v_cndmask_b32_e32 v0, v0, v1, vcc
	v_rsq_f32_e32 v0, v0
	s_add_i32 s2, s16, 0xffff0000
	s_lshr_b32 s90, s2, 5
	s_ashr_i32 s18, s16, 11
	s_lshl_b64 s[2:3], s[90:91], 17
	s_add_u32 s2, s27, s2
	v_or_b32_e32 v1, s16, v163
	v_mul_f32_e32 v2, 0x45800000, v0
	s_addc_u32 s3, s26, s3
	v_mov_b32_e32 v185, v97
	v_cndmask_b32_e32 v186, v0, v2, vcc
	v_cmp_gt_i32_e64 s[10:11], s72, v1
	v_lshl_add_u64 v[0:1], s[2:3], 0, v[184:185]
	s_mov_b64 s[2:3], 0x18000
	s_ashr_i32 s19, s18, 31
	v_bitop3_b32 v2, s16, v217, v163 bitop3:0xc8
	v_lshl_add_u64 v[188:189], v[0:1], 0, s[2:3]
	s_lshl_b64 s[2:3], s[18:19], 17
	v_add_u32_e32 v96, 0xfffff880, v2
	s_add_u32 s2, s33, s2
	s_addc_u32 s3, s49, s3
	v_lshlrev_b64 v[0:1], 10, v[96:97]
	v_cmp_lt_u32_e64 s[12:13], s86, v2
	v_lshl_add_u64 v[190:191], s[2:3], 0, v[0:1]
	v_pk_fma_f32 v[136:137], v[136:137], v[186:187], v[152:153] op_sel_hi:[1,0,1]
	v_pk_fma_f32 v[134:135], v[134:135], v[186:187], v[150:151] op_sel_hi:[1,0,1]
	v_pk_fma_f32 v[132:133], v[132:133], v[186:187], v[148:149] op_sel_hi:[1,0,1]
	v_pk_fma_f32 v[130:131], v[130:131], v[186:187], v[146:147] op_sel_hi:[1,0,1]
	s_cmp_lt_i32 s35, 1
	s_mov_b64 s[14:15], -1
	s_cbranch_scc1 .LBB0_1104
	v_mov_b64_e32 v[4:5], v[130:131]
	v_mov_b64_e32 v[0:1], v[134:135]
	s_cmp_gt_i32 s35, 3
	v_mov_b64_e32 v[6:7], v[132:133]
	v_mov_b64_e32 v[2:3], v[136:137]
	s_cbranch_scc1 .LBB0_1103
	s_cmp_lg_u32 s35, 1
	s_cbranch_scc0 .LBB0_1100
	v_lshlrev_b64 v[0:1], 2, v[182:183]
	v_lshl_add_u64 v[2:3], v[188:189], 0, v[0:1]
	v_lshl_add_u64 v[0:1], v[190:191], 0, v[0:1]
	v_cndmask_b32_e64 v0, 0, v0, s[12:13]
	v_cndmask_b32_e64 v1, 0, v1, s[12:13]
	v_cndmask_b32_e64 v1, v3, v1, s[10:11]
	v_cndmask_b32_e64 v0, v2, v0, s[10:11]
	v_cmp_ne_u64_e32 vcc, 0, v[0:1]
	s_and_saveexec_b64 s[14:15], vcc
	s_cbranch_execz .LBB0_1099
	global_store_dwordx4 v[0:1], v[134:137], off
	global_store_dwordx4 v[0:1], v[130:133], off offset:16

.Lfi_kv:
	v_readlane_b32 s10, v252, 42
	v_add_u32_e32 v1, s71, v208
	s_add_i32 s10, s10, s71
	v_add_u32_e32 v0, s10, v209
	ds_read_b128 v[186:189], v1
	ds_read_b128 v[190:193], v1 offset:256
	ds_read_b128 v[194:197], v1 offset:512
	ds_read_b128 v[198:201], v1 offset:768
	ds_read_b128 v[202:205], v1 offset:2048
	ds_read_b128 v[222:225], v1 offset:2304
	ds_read_b128 v[226:229], v1 offset:2560
	ds_read_b128 v[230:233], v1 offset:2816
	ds_read_b128 v[150:153], v0 offset:4096
	ds_read_b128 v[146:149], v0 offset:4112
	ds_read_b128 v[142:145], v0 offset:4224
	ds_read_b128 v[138:141], v0 offset:4240
	s_cmp_eq_u32 s35, 2
	s_cselect_b32 s12, s52, s54
	s_cselect_b32 s13, s53, s55
	s_cselect_b32 s18, s37, s33
	s_cselect_b32 s19, s49, s74
	s_lshl_b32 s14, s36, 8
	s_add_i32 s14, s14, s20
	s_lshl_b32 s14, s14, 9
	s_add_u32 s12, s12, s14
	s_addc_u32 s13, s13, 0
	v_add_u32_e32 v2, v182, v162
	v_lshlrev_b32_e32 v2, 1, v2
	v_lshl_add_u32 v246, v207, 9, v2
	v_add_u32_e32 v247, 0x1000, v246
	s_lshr_b32 s14, s36, 3
	s_lshl_b32 s14, s14, 7
	s_add_i32 s14, s14, s20
	s_lshl_b32 s14, s14, 10
	s_add_u32 s18, s18, s14
	s_addc_u32 s19, s19, 0
	v_lshlrev_b32_e32 v3, 10, v163
	v_lshl_add_u32 v3, v182, 2, v3
	s_and_b32 s14, s36, 7
	s_waitcnt lgkmcnt(0)
	s_cmp_eq_u32 s14, 7
	s_cbranch_scc1 .Lfi_kv_win
	v_add_f32_e32 v4, v186, v187
	v_add_f32_e32 v5, v188, v189
	v_add_f32_e32 v4, v4, v5
	v_fmamk_f32 v4, v4, 0x3a800000, v212
	v_rsq_f32_e32 v6, v4
	s_nop 1
	v_pk_fma_f32 v[136:137], v[136:137], v[6:7], v[152:153] op_sel_hi:[1,0,1]
	v_pk_fma_f32 v[134:135], v[134:135], v[6:7], v[150:151] op_sel_hi:[1,0,1]
	v_pk_fma_f32 v[132:133], v[132:133], v[6:7], v[148:149] op_sel_hi:[1,0,1]
	v_pk_fma_f32 v[130:131], v[130:131], v[6:7], v[146:147] op_sel_hi:[1,0,1]
	v_pk_fma_f32 v[128:129], v[128:129], v[6:7], v[144:145] op_sel_hi:[1,0,1]
	v_pk_fma_f32 v[126:127], v[126:127], v[6:7], v[142:143] op_sel_hi:[1,0,1]
	v_pk_fma_f32 v[124:125], v[124:125], v[6:7], v[140:141] op_sel_hi:[1,0,1]
	v_pk_fma_f32 v[122:123], v[122:123], v[6:7], v[138:139] op_sel_hi:[1,0,1]
	v_cvt_pk_bf16_f32 v234, v134, v135
	v_cvt_pk_bf16_f32 v235, v136, v137
	v_cvt_pk_bf16_f32 v236, v130, v131
	v_cvt_pk_bf16_f32 v237, v132, v133
	v_cvt_pk_bf16_f32 v238, v126, v127
	v_cvt_pk_bf16_f32 v239, v128, v129
	v_cvt_pk_bf16_f32 v240, v122, v123
	v_cvt_pk_bf16_f32 v241, v124, v125
	s_mov_b64 vcc, s[6:7]
	v_cndmask_b32_dpp v134, v238, v234, vcc row_ror:8 row_mask:0xf bank_mask:0xf
	v_cndmask_b32_dpp v135, v239, v235, vcc row_ror:8 row_mask:0xf bank_mask:0xf
	v_cndmask_b32_dpp v136, v240, v236, vcc row_ror:8 row_mask:0xf bank_mask:0xf
	v_cndmask_b32_dpp v137, v241, v237, vcc row_ror:8 row_mask:0xf bank_mask:0xf
	s_not_b64 vcc, s[6:7]
	v_cndmask_b32_dpp v130, v234, v238, vcc row_ror:8 row_mask:0xf bank_mask:0xf
	v_cndmask_b32_dpp v131, v235, v239, vcc row_ror:8 row_mask:0xf bank_mask:0xf
	v_cndmask_b32_dpp v132, v236, v240, vcc row_ror:8 row_mask:0xf bank_mask:0xf
	v_cndmask_b32_dpp v133, v237, v241, vcc row_ror:8 row_mask:0xf bank_mask:0xf
	global_store_dwordx4 v246, v[134:137], s[12:13]
	global_store_dwordx4 v247, v[130:133], s[12:13]
	v_add_f32_e32 v4, v190, v191
	v_add_f32_e32 v5, v192, v193
	v_add_f32_e32 v4, v4, v5
	v_fmamk_f32 v4, v4, 0x3a800000, v212
	v_rsq_f32_e32 v6, v4
	s_add_u32 s12, s12, 0x2000
	s_addc_u32 s13, s13, 0
	v_pk_fma_f32 v[120:121], v[120:121], v[6:7], v[152:153] op_sel_hi:[1,0,1]
	v_pk_fma_f32 v[118:119], v[118:119], v[6:7], v[150:151] op_sel_hi:[1,0,1]
	v_pk_fma_f32 v[116:117], v[116:117], v[6:7], v[148:149] op_sel_hi:[1,0,1]
	v_pk_fma_f32 v[114:115], v[114:115], v[6:7], v[146:147] op_sel_hi:[1,0,1]
	v_pk_fma_f32 v[112:113], v[112:113], v[6:7], v[144:145] op_sel_hi:[1,0,1]
	v_pk_fma_f32 v[110:111], v[110:111], v[6:7], v[142:143] op_sel_hi:[1,0,1]
	v_pk_fma_f32 v[108:109], v[108:109], v[6:7], v[140:141] op_sel_hi:[1,0,1]
	v_pk_fma_f32 v[106:107], v[106:107], v[6:7], v[138:139] op_sel_hi:[1,0,1]
	v_cvt_pk_bf16_f32 v234, v118, v119
	v_cvt_pk_bf16_f32 v235, v120, v121
	v_cvt_pk_bf16_f32 v236, v114, v115
	v_cvt_pk_bf16_f32 v237, v116, v117
	v_cvt_pk_bf16_f32 v238, v110, v111
	v_cvt_pk_bf16_f32 v239, v112, v113
	v_cvt_pk_bf16_f32 v240, v106, v107
	v_cvt_pk_bf16_f32 v241, v108, v109
	s_mov_b64 vcc, s[6:7]
	v_cndmask_b32_dpp v118, v238, v234, vcc row_ror:8 row_mask:0xf bank_mask:0xf
	v_cndmask_b32_dpp v119, v239, v235, vcc row_ror:8 row_mask:0xf bank_mask:0xf
	v_cndmask_b32_dpp v120, v240, v236, vcc row_ror:8 row_mask:0xf bank_mask:0xf
	v_cndmask_b32_dpp v121, v241, v237, vcc row_ror:8 row_mask:0xf bank_mask:0xf
	s_not_b64 vcc, s[6:7]
	v_cndmask_b32_dpp v114, v234, v238, vcc row_ror:8 row_mask:0xf bank_mask:0xf
	v_cndmask_b32_dpp v115, v235, v239, vcc row_ror:8 row_mask:0xf bank_mask:0xf
	v_cndmask_b32_dpp v116, v236, v240, vcc row_ror:8 row_mask:0xf bank_mask:0xf
	v_cndmask_b32_dpp v117, v237, v241, vcc row_ror:8 row_mask:0xf bank_mask:0xf
	global_store_dwordx4 v246, v[118:121], s[12:13]
	global_store_dwordx4 v247, v[114:117], s[12:13]
	v_add_f32_e32 v4, v194, v195
	v_add_f32_e32 v5, v196, v197
	v_add_f32_e32 v4, v4, v5
	v_fmamk_f32 v4, v4, 0x3a800000, v212
	v_rsq_f32_e32 v6, v4
	s_add_u32 s12, s12, 0x2000
	s_addc_u32 s13, s13, 0
	v_pk_fma_f32 v[104:105], v[104:105], v[6:7], v[152:153] op_sel_hi:[1,0,1]
	v_pk_fma_f32 v[102:103], v[102:103], v[6:7], v[150:151] op_sel_hi:[1,0,1]
	v_pk_fma_f32 v[100:101], v[100:101], v[6:7], v[148:149] op_sel_hi:[1,0,1]
	v_pk_fma_f32 v[98:99], v[98:99], v[6:7], v[146:147] op_sel_hi:[1,0,1]
	v_pk_fma_f32 v[94:95], v[94:95], v[6:7], v[144:145] op_sel_hi:[1,0,1]
	v_pk_fma_f32 v[92:93], v[92:93], v[6:7], v[142:143] op_sel_hi:[1,0,1]
	v_pk_fma_f32 v[90:91], v[90:91], v[6:7], v[140:141] op_sel_hi:[1,0,1]
	v_pk_fma_f32 v[88:89], v[88:89], v[6:7], v[138:139] op_sel_hi:[1,0,1]
	v_cvt_pk_bf16_f32 v234, v102, v103
	v_cvt_pk_bf16_f32 v235, v104, v105
	v_cvt_pk_bf16_f32 v236, v98, v99
	v_cvt_pk_bf16_f32 v237, v100, v101
	v_cvt_pk_bf16_f32 v238, v92, v93
	v_cvt_pk_bf16_f32 v239, v94, v95
	v_cvt_pk_bf16_f32 v240, v88, v89
	v_cvt_pk_bf16_f32 v241, v90, v91
	s_mov_b64 vcc, s[6:7]
	v_cndmask_b32_dpp v102, v238, v234, vcc row_ror:8 row_mask:0xf bank_mask:0xf
	v_cndmask_b32_dpp v103, v239, v235, vcc row_ror:8 row_mask:0xf bank_mask:0xf
	v_cndmask_b32_dpp v104, v240, v236, vcc row_ror:8 row_mask:0xf bank_mask:0xf
	v_cndmask_b32_dpp v105, v241, v237, vcc row_ror:8 row_mask:0xf bank_mask:0xf
	s_not_b64 vcc, s[6:7]
	v_cndmask_b32_dpp v98, v234, v238, vcc row_ror:8 row_mask:0xf bank_mask:0xf
	v_cndmask_b32_dpp v99, v235, v239, vcc row_ror:8 row_mask:0xf bank_mask:0xf
	v_cndmask_b32_dpp v100, v236, v240, vcc row_ror:8 row_mask:0xf bank_mask:0xf
	v_cndmask_b32_dpp v101, v237, v241, vcc row_ror:8 row_mask:0xf bank_mask:0xf
	global_store_dwordx4 v246, v[102:105], s[12:13]
	global_store_dwordx4 v247, v[98:101], s[12:13]
	v_add_f32_e32 v4, v198, v199
	v_add_f32_e32 v5, v200, v201
	v_add_f32_e32 v4, v4, v5
	v_fmamk_f32 v4, v4, 0x3a800000, v212
	v_rsq_f32_e32 v6, v4
	s_add_u32 s12, s12, 0x2000
	s_addc_u32 s13, s13, 0
	v_pk_fma_f32 v[86:87], v[86:87], v[6:7], v[152:153] op_sel_hi:[1,0,1]
	v_pk_fma_f32 v[84:85], v[84:85], v[6:7], v[150:151] op_sel_hi:[1,0,1]
	v_pk_fma_f32 v[82:83], v[82:83], v[6:7], v[148:149] op_sel_hi:[1,0,1]
	v_pk_fma_f32 v[80:81], v[80:81], v[6:7], v[146:147] op_sel_hi:[1,0,1]
	v_pk_fma_f32 v[78:79], v[78:79], v[6:7], v[144:145] op_sel_hi:[1,0,1]
	v_pk_fma_f32 v[76:77], v[76:77], v[6:7], v[142:143] op_sel_hi:[1,0,1]
	v_pk_fma_f32 v[74:75], v[74:75], v[6:7], v[140:141] op_sel_hi:[1,0,1]
	v_pk_fma_f32 v[72:73], v[72:73], v[6:7], v[138:139] op_sel_hi:[1,0,1]
	v_cvt_pk_bf16_f32 v234, v84, v85
	v_cvt_pk_bf16_f32 v235, v86, v87
	v_cvt_pk_bf16_f32 v236, v80, v81
	v_cvt_pk_bf16_f32 v237, v82, v83
	v_cvt_pk_bf16_f32 v238, v76, v77
	v_cvt_pk_bf16_f32 v239, v78, v79
	v_cvt_pk_bf16_f32 v240, v72, v73
	v_cvt_pk_bf16_f32 v241, v74, v75
	s_mov_b64 vcc, s[6:7]
	v_cndmask_b32_dpp v84, v238, v234, vcc row_ror:8 row_mask:0xf bank_mask:0xf
	v_cndmask_b32_dpp v85, v239, v235, vcc row_ror:8 row_mask:0xf bank_mask:0xf
	v_cndmask_b32_dpp v86, v240, v236, vcc row_ror:8 row_mask:0xf bank_mask:0xf
	v_cndmask_b32_dpp v87, v241, v237, vcc row_ror:8 row_mask:0xf bank_mask:0xf
	s_not_b64 vcc, s[6:7]
	v_cndmask_b32_dpp v80, v234, v238, vcc row_ror:8 row_mask:0xf bank_mask:0xf
	v_cndmask_b32_dpp v81, v235, v239, vcc row_ror:8 row_mask:0xf bank_mask:0xf
	v_cndmask_b32_dpp v82, v236, v240, vcc row_ror:8 row_mask:0xf bank_mask:0xf
	v_cndmask_b32_dpp v83, v237, v241, vcc row_ror:8 row_mask:0xf bank_mask:0xf
	global_store_dwordx4 v246, v[84:87], s[12:13]
	global_store_dwordx4 v247, v[80:83], s[12:13]
	v_add_f32_e32 v4, v202, v203
	v_add_f32_e32 v5, v204, v205
	v_add_f32_e32 v4, v4, v5
	v_fmamk_f32 v4, v4, 0x3a800000, v212
	v_rsq_f32_e32 v6, v4
	s_add_u32 s12, s12, 0xa000
	s_addc_u32 s13, s13, 0
	v_pk_fma_f32 v[70:71], v[70:71], v[6:7], v[152:153] op_sel_hi:[1,0,1]
	v_pk_fma_f32 v[68:69], v[68:69], v[6:7], v[150:151] op_sel_hi:[1,0,1]
	v_pk_fma_f32 v[66:67], v[66:67], v[6:7], v[148:149] op_sel_hi:[1,0,1]
	v_pk_fma_f32 v[64:65], v[64:65], v[6:7], v[146:147] op_sel_hi:[1,0,1]
	v_pk_fma_f32 v[62:63], v[62:63], v[6:7], v[144:145] op_sel_hi:[1,0,1]
	v_pk_fma_f32 v[60:61], v[60:61], v[6:7], v[142:143] op_sel_hi:[1,0,1]
	v_pk_fma_f32 v[58:59], v[58:59], v[6:7], v[140:141] op_sel_hi:[1,0,1]
	v_pk_fma_f32 v[56:57], v[56:57], v[6:7], v[138:139] op_sel_hi:[1,0,1]
	v_cvt_pk_bf16_f32 v234, v68, v69
	v_cvt_pk_bf16_f32 v235, v70, v71
	v_cvt_pk_bf16_f32 v236, v64, v65
	v_cvt_pk_bf16_f32 v237, v66, v67
	v_cvt_pk_bf16_f32 v238, v60, v61
	v_cvt_pk_bf16_f32 v239, v62, v63
	v_cvt_pk_bf16_f32 v240, v56, v57
	v_cvt_pk_bf16_f32 v241, v58, v59
	s_mov_b64 vcc, s[6:7]
	v_cndmask_b32_dpp v68, v238, v234, vcc row_ror:8 row_mask:0xf bank_mask:0xf
	v_cndmask_b32_dpp v69, v239, v235, vcc row_ror:8 row_mask:0xf bank_mask:0xf
	v_cndmask_b32_dpp v70, v240, v236, vcc row_ror:8 row_mask:0xf bank_mask:0xf
	v_cndmask_b32_dpp v71, v241, v237, vcc row_ror:8 row_mask:0xf bank_mask:0xf
	s_not_b64 vcc, s[6:7]
	v_cndmask_b32_dpp v64, v234, v238, vcc row_ror:8 row_mask:0xf bank_mask:0xf
	v_cndmask_b32_dpp v65, v235, v239, vcc row_ror:8 row_mask:0xf bank_mask:0xf
	v_cndmask_b32_dpp v66, v236, v240, vcc row_ror:8 row_mask:0xf bank_mask:0xf
	v_cndmask_b32_dpp v67, v237, v241, vcc row_ror:8 row_mask:0xf bank_mask:0xf
	global_store_dwordx4 v246, v[68:71], s[12:13]
	global_store_dwordx4 v247, v[64:67], s[12:13]
	v_add_f32_e32 v4, v222, v223
	v_add_f32_e32 v5, v224, v225
	v_add_f32_e32 v4, v4, v5
	v_fmamk_f32 v4, v4, 0x3a800000, v212
	v_rsq_f32_e32 v6, v4
	s_add_u32 s12, s12, 0x2000
	s_addc_u32 s13, s13, 0
	v_pk_fma_f32 v[54:55], v[54:55], v[6:7], v[152:153] op_sel_hi:[1,0,1]
	v_pk_fma_f32 v[52:53], v[52:53], v[6:7], v[150:151] op_sel_hi:[1,0,1]
	v_pk_fma_f32 v[50:51], v[50:51], v[6:7], v[148:149] op_sel_hi:[1,0,1]
	v_pk_fma_f32 v[48:49], v[48:49], v[6:7], v[146:147] op_sel_hi:[1,0,1]
	v_pk_fma_f32 v[46:47], v[46:47], v[6:7], v[144:145] op_sel_hi:[1,0,1]
	v_pk_fma_f32 v[44:45], v[44:45], v[6:7], v[142:143] op_sel_hi:[1,0,1]
	v_pk_fma_f32 v[42:43], v[42:43], v[6:7], v[140:141] op_sel_hi:[1,0,1]
	v_pk_fma_f32 v[40:41], v[40:41], v[6:7], v[138:139] op_sel_hi:[1,0,1]
	v_cvt_pk_bf16_f32 v234, v52, v53
	v_cvt_pk_bf16_f32 v235, v54, v55
	v_cvt_pk_bf16_f32 v236, v48, v49
	v_cvt_pk_bf16_f32 v237, v50, v51
	v_cvt_pk_bf16_f32 v238, v44, v45
	v_cvt_pk_bf16_f32 v239, v46, v47
	v_cvt_pk_bf16_f32 v240, v40, v41
	v_cvt_pk_bf16_f32 v241, v42, v43
	s_mov_b64 vcc, s[6:7]
	v_cndmask_b32_dpp v52, v238, v234, vcc row_ror:8 row_mask:0xf bank_mask:0xf
	v_cndmask_b32_dpp v53, v239, v235, vcc row_ror:8 row_mask:0xf bank_mask:0xf
	v_cndmask_b32_dpp v54, v240, v236, vcc row_ror:8 row_mask:0xf bank_mask:0xf
	v_cndmask_b32_dpp v55, v241, v237, vcc row_ror:8 row_mask:0xf bank_mask:0xf
	s_not_b64 vcc, s[6:7]
	v_cndmask_b32_dpp v48, v234, v238, vcc row_ror:8 row_mask:0xf bank_mask:0xf
	v_cndmask_b32_dpp v49, v235, v239, vcc row_ror:8 row_mask:0xf bank_mask:0xf
	v_cndmask_b32_dpp v50, v236, v240, vcc row_ror:8 row_mask:0xf bank_mask:0xf
	v_cndmask_b32_dpp v51, v237, v241, vcc row_ror:8 row_mask:0xf bank_mask:0xf
	global_store_dwordx4 v246, v[52:55], s[12:13]
	global_store_dwordx4 v247, v[48:51], s[12:13]
	v_add_f32_e32 v4, v226, v227
	v_add_f32_e32 v5, v228, v229
	v_add_f32_e32 v4, v4, v5
	v_fmamk_f32 v4, v4, 0x3a800000, v212
	v_rsq_f32_e32 v6, v4
	s_add_u32 s12, s12, 0x2000
	s_addc_u32 s13, s13, 0
	v_pk_fma_f32 v[38:39], v[38:39], v[6:7], v[152:153] op_sel_hi:[1,0,1]
	v_pk_fma_f32 v[36:37], v[36:37], v[6:7], v[150:151] op_sel_hi:[1,0,1]
	v_pk_fma_f32 v[34:35], v[34:35], v[6:7], v[148:149] op_sel_hi:[1,0,1]
	v_pk_fma_f32 v[32:33], v[32:33], v[6:7], v[146:147] op_sel_hi:[1,0,1]
	v_pk_fma_f32 v[30:31], v[30:31], v[6:7], v[144:145] op_sel_hi:[1,0,1]
	v_pk_fma_f32 v[28:29], v[28:29], v[6:7], v[142:143] op_sel_hi:[1,0,1]
	v_pk_fma_f32 v[26:27], v[26:27], v[6:7], v[140:141] op_sel_hi:[1,0,1]
	v_pk_fma_f32 v[24:25], v[24:25], v[6:7], v[138:139] op_sel_hi:[1,0,1]
	v_cvt_pk_bf16_f32 v234, v36, v37
	v_cvt_pk_bf16_f32 v235, v38, v39
	v_cvt_pk_bf16_f32 v236, v32, v33
	v_cvt_pk_bf16_f32 v237, v34, v35
	v_cvt_pk_bf16_f32 v238, v28, v29
	v_cvt_pk_bf16_f32 v239, v30, v31
	v_cvt_pk_bf16_f32 v240, v24, v25
	v_cvt_pk_bf16_f32 v241, v26, v27
	s_mov_b64 vcc, s[6:7]
	v_cndmask_b32_dpp v36, v238, v234, vcc row_ror:8 row_mask:0xf bank_mask:0xf
	v_cndmask_b32_dpp v37, v239, v235, vcc row_ror:8 row_mask:0xf bank_mask:0xf
	v_cndmask_b32_dpp v38, v240, v236, vcc row_ror:8 row_mask:0xf bank_mask:0xf
	v_cndmask_b32_dpp v39, v241, v237, vcc row_ror:8 row_mask:0xf bank_mask:0xf
	s_not_b64 vcc, s[6:7]
	v_cndmask_b32_dpp v32, v234, v238, vcc row_ror:8 row_mask:0xf bank_mask:0xf
	v_cndmask_b32_dpp v33, v235, v239, vcc row_ror:8 row_mask:0xf bank_mask:0xf
	v_cndmask_b32_dpp v34, v236, v240, vcc row_ror:8 row_mask:0xf bank_mask:0xf
	v_cndmask_b32_dpp v35, v237, v241, vcc row_ror:8 row_mask:0xf bank_mask:0xf
	global_store_dwordx4 v246, v[36:39], s[12:13]
	global_store_dwordx4 v247, v[32:35], s[12:13]
	v_add_f32_e32 v4, v230, v231
	v_add_f32_e32 v5, v232, v233
	v_add_f32_e32 v4, v4, v5
	v_fmamk_f32 v4, v4, 0x3a800000, v212
	v_rsq_f32_e32 v6, v4
	s_add_u32 s12, s12, 0x2000
	s_addc_u32 s13, s13, 0
	v_pk_fma_f32 v[22:23], v[22:23], v[6:7], v[152:153] op_sel_hi:[1,0,1]
	v_pk_fma_f32 v[20:21], v[20:21], v[6:7], v[150:151] op_sel_hi:[1,0,1]
	v_pk_fma_f32 v[18:19], v[18:19], v[6:7], v[148:149] op_sel_hi:[1,0,1]
	v_pk_fma_f32 v[16:17], v[16:17], v[6:7], v[146:147] op_sel_hi:[1,0,1]
	v_pk_fma_f32 v[14:15], v[14:15], v[6:7], v[144:145] op_sel_hi:[1,0,1]
	v_pk_fma_f32 v[12:13], v[12:13], v[6:7], v[142:143] op_sel_hi:[1,0,1]
	v_pk_fma_f32 v[10:11], v[10:11], v[6:7], v[140:141] op_sel_hi:[1,0,1]
	v_pk_fma_f32 v[8:9], v[8:9], v[6:7], v[138:139] op_sel_hi:[1,0,1]
	v_cvt_pk_bf16_f32 v234, v20, v21
	v_cvt_pk_bf16_f32 v235, v22, v23
	v_cvt_pk_bf16_f32 v236, v16, v17
	v_cvt_pk_bf16_f32 v237, v18, v19
	v_cvt_pk_bf16_f32 v238, v12, v13
	v_cvt_pk_bf16_f32 v239, v14, v15
	v_cvt_pk_bf16_f32 v240, v8, v9
	v_cvt_pk_bf16_f32 v241, v10, v11
	s_mov_b64 vcc, s[6:7]
	v_cndmask_b32_dpp v20, v238, v234, vcc row_ror:8 row_mask:0xf bank_mask:0xf
	v_cndmask_b32_dpp v21, v239, v235, vcc row_ror:8 row_mask:0xf bank_mask:0xf
	v_cndmask_b32_dpp v22, v240, v236, vcc row_ror:8 row_mask:0xf bank_mask:0xf
	v_cndmask_b32_dpp v23, v241, v237, vcc row_ror:8 row_mask:0xf bank_mask:0xf
	s_not_b64 vcc, s[6:7]
	v_cndmask_b32_dpp v16, v234, v238, vcc row_ror:8 row_mask:0xf bank_mask:0xf
	v_cndmask_b32_dpp v17, v235, v239, vcc row_ror:8 row_mask:0xf bank_mask:0xf
	v_cndmask_b32_dpp v18, v236, v240, vcc row_ror:8 row_mask:0xf bank_mask:0xf
	v_cndmask_b32_dpp v19, v237, v241, vcc row_ror:8 row_mask:0xf bank_mask:0xf
	global_store_dwordx4 v246, v[20:23], s[12:13]
	global_store_dwordx4 v247, v[16:19], s[12:13]
	s_mov_b32 s100, 1
	s_branch .LBB0_1422
.Lfi_kv_win:
	v_add_f32_e32 v4, v186, v187
	v_add_f32_e32 v5, v188, v189
	v_add_f32_e32 v4, v4, v5
	v_fmamk_f32 v4, v4, 0x3a800000, v212
	v_rsq_f32_e32 v6, v4
	s_nop 1
	v_pk_fma_f32 v[136:137], v[136:137], v[6:7], v[152:153] op_sel_hi:[1,0,1]
	v_pk_fma_f32 v[134:135], v[134:135], v[6:7], v[150:151] op_sel_hi:[1,0,1]
	v_pk_fma_f32 v[132:133], v[132:133], v[6:7], v[148:149] op_sel_hi:[1,0,1]
	v_pk_fma_f32 v[130:131], v[130:131], v[6:7], v[146:147] op_sel_hi:[1,0,1]
	v_pk_fma_f32 v[128:129], v[128:129], v[6:7], v[144:145] op_sel_hi:[1,0,1]
	v_pk_fma_f32 v[126:127], v[126:127], v[6:7], v[142:143] op_sel_hi:[1,0,1]
	v_pk_fma_f32 v[124:125], v[124:125], v[6:7], v[140:141] op_sel_hi:[1,0,1]
	v_pk_fma_f32 v[122:123], v[122:123], v[6:7], v[138:139] op_sel_hi:[1,0,1]
	v_cvt_pk_bf16_f32 v234, v134, v135
	v_cvt_pk_bf16_f32 v235, v136, v137
	v_cvt_pk_bf16_f32 v236, v130, v131
	v_cvt_pk_bf16_f32 v237, v132, v133
	v_cvt_pk_bf16_f32 v238, v126, v127
	v_cvt_pk_bf16_f32 v239, v128, v129
	v_cvt_pk_bf16_f32 v240, v122, v123
	v_cvt_pk_bf16_f32 v241, v124, v125
	s_mov_b64 vcc, s[6:7]
	v_cndmask_b32_dpp v134, v238, v234, vcc row_ror:8 row_mask:0xf bank_mask:0xf
	v_cndmask_b32_dpp v135, v239, v235, vcc row_ror:8 row_mask:0xf bank_mask:0xf
	v_cndmask_b32_dpp v136, v240, v236, vcc row_ror:8 row_mask:0xf bank_mask:0xf
	v_cndmask_b32_dpp v137, v241, v237, vcc row_ror:8 row_mask:0xf bank_mask:0xf
	s_not_b64 vcc, s[6:7]
	v_cndmask_b32_dpp v130, v234, v238, vcc row_ror:8 row_mask:0xf bank_mask:0xf
	v_cndmask_b32_dpp v131, v235, v239, vcc row_ror:8 row_mask:0xf bank_mask:0xf
	v_cndmask_b32_dpp v132, v236, v240, vcc row_ror:8 row_mask:0xf bank_mask:0xf
	v_cndmask_b32_dpp v133, v237, v241, vcc row_ror:8 row_mask:0xf bank_mask:0xf
	global_store_dwordx4 v246, v[134:137], s[12:13]
	global_store_dwordx4 v247, v[130:133], s[12:13]
	v_add_f32_e32 v4, v190, v191
	v_add_f32_e32 v5, v192, v193
	v_add_f32_e32 v4, v4, v5
	v_fmamk_f32 v4, v4, 0x3a800000, v212
	v_rsq_f32_e32 v6, v4
	s_add_u32 s12, s12, 0x2000
	s_addc_u32 s13, s13, 0
	v_pk_fma_f32 v[120:121], v[120:121], v[6:7], v[152:153] op_sel_hi:[1,0,1]
	v_pk_fma_f32 v[118:119], v[118:119], v[6:7], v[150:151] op_sel_hi:[1,0,1]
	v_pk_fma_f32 v[116:117], v[116:117], v[6:7], v[148:149] op_sel_hi:[1,0,1]
	v_pk_fma_f32 v[114:115], v[114:115], v[6:7], v[146:147] op_sel_hi:[1,0,1]
	v_pk_fma_f32 v[112:113], v[112:113], v[6:7], v[144:145] op_sel_hi:[1,0,1]
	v_pk_fma_f32 v[110:111], v[110:111], v[6:7], v[142:143] op_sel_hi:[1,0,1]
	v_pk_fma_f32 v[108:109], v[108:109], v[6:7], v[140:141] op_sel_hi:[1,0,1]
	v_pk_fma_f32 v[106:107], v[106:107], v[6:7], v[138:139] op_sel_hi:[1,0,1]
	v_cvt_pk_bf16_f32 v234, v118, v119
	v_cvt_pk_bf16_f32 v235, v120, v121
	v_cvt_pk_bf16_f32 v236, v114, v115
	v_cvt_pk_bf16_f32 v237, v116, v117
	v_cvt_pk_bf16_f32 v238, v110, v111
	v_cvt_pk_bf16_f32 v239, v112, v113
	v_cvt_pk_bf16_f32 v240, v106, v107
	v_cvt_pk_bf16_f32 v241, v108, v109
	s_mov_b64 vcc, s[6:7]
	v_cndmask_b32_dpp v118, v238, v234, vcc row_ror:8 row_mask:0xf bank_mask:0xf
	v_cndmask_b32_dpp v119, v239, v235, vcc row_ror:8 row_mask:0xf bank_mask:0xf
	v_cndmask_b32_dpp v120, v240, v236, vcc row_ror:8 row_mask:0xf bank_mask:0xf
	v_cndmask_b32_dpp v121, v241, v237, vcc row_ror:8 row_mask:0xf bank_mask:0xf
	s_not_b64 vcc, s[6:7]
	v_cndmask_b32_dpp v114, v234, v238, vcc row_ror:8 row_mask:0xf bank_mask:0xf
	v_cndmask_b32_dpp v115, v235, v239, vcc row_ror:8 row_mask:0xf bank_mask:0xf
	v_cndmask_b32_dpp v116, v236, v240, vcc row_ror:8 row_mask:0xf bank_mask:0xf
	v_cndmask_b32_dpp v117, v237, v241, vcc row_ror:8 row_mask:0xf bank_mask:0xf
	global_store_dwordx4 v246, v[118:121], s[12:13]
	global_store_dwordx4 v247, v[114:117], s[12:13]
	v_add_f32_e32 v4, v194, v195
	v_add_f32_e32 v5, v196, v197
	v_add_f32_e32 v4, v4, v5
	v_fmamk_f32 v4, v4, 0x3a800000, v212
	v_rsq_f32_e32 v6, v4
	s_add_u32 s12, s12, 0x2000
	s_addc_u32 s13, s13, 0
	v_pk_fma_f32 v[104:105], v[104:105], v[6:7], v[152:153] op_sel_hi:[1,0,1]
	v_pk_fma_f32 v[102:103], v[102:103], v[6:7], v[150:151] op_sel_hi:[1,0,1]
	v_pk_fma_f32 v[100:101], v[100:101], v[6:7], v[148:149] op_sel_hi:[1,0,1]
	v_pk_fma_f32 v[98:99], v[98:99], v[6:7], v[146:147] op_sel_hi:[1,0,1]
	v_pk_fma_f32 v[94:95], v[94:95], v[6:7], v[144:145] op_sel_hi:[1,0,1]
	v_pk_fma_f32 v[92:93], v[92:93], v[6:7], v[142:143] op_sel_hi:[1,0,1]
	v_pk_fma_f32 v[90:91], v[90:91], v[6:7], v[140:141] op_sel_hi:[1,0,1]
	v_pk_fma_f32 v[88:89], v[88:89], v[6:7], v[138:139] op_sel_hi:[1,0,1]
	v_cvt_pk_bf16_f32 v234, v102, v103
	v_cvt_pk_bf16_f32 v235, v104, v105
	v_cvt_pk_bf16_f32 v236, v98, v99
	v_cvt_pk_bf16_f32 v237, v100, v101
	v_cvt_pk_bf16_f32 v238, v92, v93
	v_cvt_pk_bf16_f32 v239, v94, v95
	v_cvt_pk_bf16_f32 v240, v88, v89
	v_cvt_pk_bf16_f32 v241, v90, v91
	s_mov_b64 vcc, s[6:7]
	v_cndmask_b32_dpp v102, v238, v234, vcc row_ror:8 row_mask:0xf bank_mask:0xf
	v_cndmask_b32_dpp v103, v239, v235, vcc row_ror:8 row_mask:0xf bank_mask:0xf
	v_cndmask_b32_dpp v104, v240, v236, vcc row_ror:8 row_mask:0xf bank_mask:0xf
	v_cndmask_b32_dpp v105, v241, v237, vcc row_ror:8 row_mask:0xf bank_mask:0xf
	s_not_b64 vcc, s[6:7]
	v_cndmask_b32_dpp v98, v234, v238, vcc row_ror:8 row_mask:0xf bank_mask:0xf
	v_cndmask_b32_dpp v99, v235, v239, vcc row_ror:8 row_mask:0xf bank_mask:0xf
	v_cndmask_b32_dpp v100, v236, v240, vcc row_ror:8 row_mask:0xf bank_mask:0xf
	v_cndmask_b32_dpp v101, v237, v241, vcc row_ror:8 row_mask:0xf bank_mask:0xf
	global_store_dwordx4 v246, v[102:105], s[12:13]
	global_store_dwordx4 v247, v[98:101], s[12:13]
	v_add_f32_e32 v4, v198, v199
	v_add_f32_e32 v5, v200, v201
	v_add_f32_e32 v4, v4, v5
	v_fmamk_f32 v4, v4, 0x3a800000, v212
	v_rsq_f32_e32 v6, v4
	s_add_u32 s12, s12, 0x2000
	s_addc_u32 s13, s13, 0
	v_pk_fma_f32 v[86:87], v[86:87], v[6:7], v[152:153] op_sel_hi:[1,0,1]
	v_pk_fma_f32 v[84:85], v[84:85], v[6:7], v[150:151] op_sel_hi:[1,0,1]
	v_pk_fma_f32 v[82:83], v[82:83], v[6:7], v[148:149] op_sel_hi:[1,0,1]
	v_pk_fma_f32 v[80:81], v[80:81], v[6:7], v[146:147] op_sel_hi:[1,0,1]
	v_pk_fma_f32 v[78:79], v[78:79], v[6:7], v[144:145] op_sel_hi:[1,0,1]
	v_pk_fma_f32 v[76:77], v[76:77], v[6:7], v[142:143] op_sel_hi:[1,0,1]
	v_pk_fma_f32 v[74:75], v[74:75], v[6:7], v[140:141] op_sel_hi:[1,0,1]
	v_pk_fma_f32 v[72:73], v[72:73], v[6:7], v[138:139] op_sel_hi:[1,0,1]
	v_cvt_pk_bf16_f32 v234, v84, v85
	v_cvt_pk_bf16_f32 v235, v86, v87
	v_cvt_pk_bf16_f32 v236, v80, v81
	v_cvt_pk_bf16_f32 v237, v82, v83
	v_cvt_pk_bf16_f32 v238, v76, v77
	v_cvt_pk_bf16_f32 v239, v78, v79
	v_cvt_pk_bf16_f32 v240, v72, v73
	v_cvt_pk_bf16_f32 v241, v74, v75
	s_mov_b64 vcc, s[6:7]
	v_cndmask_b32_dpp v84, v238, v234, vcc row_ror:8 row_mask:0xf bank_mask:0xf
	v_cndmask_b32_dpp v85, v239, v235, vcc row_ror:8 row_mask:0xf bank_mask:0xf
	v_cndmask_b32_dpp v86, v240, v236, vcc row_ror:8 row_mask:0xf bank_mask:0xf
	v_cndmask_b32_dpp v87, v241, v237, vcc row_ror:8 row_mask:0xf bank_mask:0xf
	s_not_b64 vcc, s[6:7]
	v_cndmask_b32_dpp v80, v234, v238, vcc row_ror:8 row_mask:0xf bank_mask:0xf
	v_cndmask_b32_dpp v81, v235, v239, vcc row_ror:8 row_mask:0xf bank_mask:0xf
	v_cndmask_b32_dpp v82, v236, v240, vcc row_ror:8 row_mask:0xf bank_mask:0xf
	v_cndmask_b32_dpp v83, v237, v241, vcc row_ror:8 row_mask:0xf bank_mask:0xf
	global_store_dwordx4 v246, v[84:87], s[12:13]
	global_store_dwordx4 v247, v[80:83], s[12:13]
	v_add_f32_e32 v4, v202, v203
	v_add_f32_e32 v5, v204, v205
	v_add_f32_e32 v4, v4, v5
	v_fmamk_f32 v4, v4, 0x3a800000, v212
	v_rsq_f32_e32 v6, v4
	s_add_u32 s12, s12, 0xa000
	s_addc_u32 s13, s13, 0
	v_pk_fma_f32 v[70:71], v[70:71], v[6:7], v[152:153] op_sel_hi:[1,0,1]
	v_pk_fma_f32 v[68:69], v[68:69], v[6:7], v[150:151] op_sel_hi:[1,0,1]
	v_pk_fma_f32 v[66:67], v[66:67], v[6:7], v[148:149] op_sel_hi:[1,0,1]
	v_pk_fma_f32 v[64:65], v[64:65], v[6:7], v[146:147] op_sel_hi:[1,0,1]
	v_pk_fma_f32 v[62:63], v[62:63], v[6:7], v[144:145] op_sel_hi:[1,0,1]
	v_pk_fma_f32 v[60:61], v[60:61], v[6:7], v[142:143] op_sel_hi:[1,0,1]
	v_pk_fma_f32 v[58:59], v[58:59], v[6:7], v[140:141] op_sel_hi:[1,0,1]
	v_pk_fma_f32 v[56:57], v[56:57], v[6:7], v[138:139] op_sel_hi:[1,0,1]
	global_store_dwordx4 v3, v[68:71], s[18:19]
	global_store_dwordx4 v3, v[64:67], s[18:19] offset:16
	global_store_dwordx4 v3, v[60:63], s[18:19] offset:128
	global_store_dwordx4 v3, v[56:59], s[18:19] offset:144
	v_cvt_pk_bf16_f32 v234, v68, v69
	v_cvt_pk_bf16_f32 v235, v70, v71
	v_cvt_pk_bf16_f32 v236, v64, v65
	v_cvt_pk_bf16_f32 v237, v66, v67
	v_cvt_pk_bf16_f32 v238, v60, v61
	v_cvt_pk_bf16_f32 v239, v62, v63
	v_cvt_pk_bf16_f32 v240, v56, v57
	v_cvt_pk_bf16_f32 v241, v58, v59
	s_mov_b64 vcc, s[6:7]
	v_cndmask_b32_dpp v68, v238, v234, vcc row_ror:8 row_mask:0xf bank_mask:0xf
	v_cndmask_b32_dpp v69, v239, v235, vcc row_ror:8 row_mask:0xf bank_mask:0xf
	v_cndmask_b32_dpp v70, v240, v236, vcc row_ror:8 row_mask:0xf bank_mask:0xf
	v_cndmask_b32_dpp v71, v241, v237, vcc row_ror:8 row_mask:0xf bank_mask:0xf
	s_not_b64 vcc, s[6:7]
	v_cndmask_b32_dpp v64, v234, v238, vcc row_ror:8 row_mask:0xf bank_mask:0xf
	v_cndmask_b32_dpp v65, v235, v239, vcc row_ror:8 row_mask:0xf bank_mask:0xf
	v_cndmask_b32_dpp v66, v236, v240, vcc row_ror:8 row_mask:0xf bank_mask:0xf
	v_cndmask_b32_dpp v67, v237, v241, vcc row_ror:8 row_mask:0xf bank_mask:0xf
	global_store_dwordx4 v246, v[68:71], s[12:13]
	global_store_dwordx4 v247, v[64:67], s[12:13]
	v_add_f32_e32 v4, v222, v223
	v_add_f32_e32 v5, v224, v225
	v_add_f32_e32 v4, v4, v5
	v_fmamk_f32 v4, v4, 0x3a800000, v212
	v_rsq_f32_e32 v6, v4
	s_add_u32 s12, s12, 0x2000
	s_addc_u32 s13, s13, 0
	v_pk_fma_f32 v[54:55], v[54:55], v[6:7], v[152:153] op_sel_hi:[1,0,1]
	v_pk_fma_f32 v[52:53], v[52:53], v[6:7], v[150:151] op_sel_hi:[1,0,1]
	v_pk_fma_f32 v[50:51], v[50:51], v[6:7], v[148:149] op_sel_hi:[1,0,1]
	v_pk_fma_f32 v[48:49], v[48:49], v[6:7], v[146:147] op_sel_hi:[1,0,1]
	v_pk_fma_f32 v[46:47], v[46:47], v[6:7], v[144:145] op_sel_hi:[1,0,1]
	v_pk_fma_f32 v[44:45], v[44:45], v[6:7], v[142:143] op_sel_hi:[1,0,1]
	v_pk_fma_f32 v[42:43], v[42:43], v[6:7], v[140:141] op_sel_hi:[1,0,1]
	v_pk_fma_f32 v[40:41], v[40:41], v[6:7], v[138:139] op_sel_hi:[1,0,1]
	s_add_u32 s18, s18, 0x4000
	s_addc_u32 s19, s19, 0
	global_store_dwordx4 v3, v[52:55], s[18:19]
	global_store_dwordx4 v3, v[48:51], s[18:19] offset:16
	global_store_dwordx4 v3, v[44:47], s[18:19] offset:128
	global_store_dwordx4 v3, v[40:43], s[18:19] offset:144
	v_cvt_pk_bf16_f32 v234, v52, v53
	v_cvt_pk_bf16_f32 v235, v54, v55
	v_cvt_pk_bf16_f32 v236, v48, v49
	v_cvt_pk_bf16_f32 v237, v50, v51
	v_cvt_pk_bf16_f32 v238, v44, v45
	v_cvt_pk_bf16_f32 v239, v46, v47
	v_cvt_pk_bf16_f32 v240, v40, v41
	v_cvt_pk_bf16_f32 v241, v42, v43
	s_mov_b64 vcc, s[6:7]
	v_cndmask_b32_dpp v52, v238, v234, vcc row_ror:8 row_mask:0xf bank_mask:0xf
	v_cndmask_b32_dpp v53, v239, v235, vcc row_ror:8 row_mask:0xf bank_mask:0xf
	v_cndmask_b32_dpp v54, v240, v236, vcc row_ror:8 row_mask:0xf bank_mask:0xf
	v_cndmask_b32_dpp v55, v241, v237, vcc row_ror:8 row_mask:0xf bank_mask:0xf
	s_not_b64 vcc, s[6:7]
	v_cndmask_b32_dpp v48, v234, v238, vcc row_ror:8 row_mask:0xf bank_mask:0xf
	v_cndmask_b32_dpp v49, v235, v239, vcc row_ror:8 row_mask:0xf bank_mask:0xf
	v_cndmask_b32_dpp v50, v236, v240, vcc row_ror:8 row_mask:0xf bank_mask:0xf
	v_cndmask_b32_dpp v51, v237, v241, vcc row_ror:8 row_mask:0xf bank_mask:0xf
	global_store_dwordx4 v246, v[52:55], s[12:13]
	global_store_dwordx4 v247, v[48:51], s[12:13]
	v_add_f32_e32 v4, v226, v227
	v_add_f32_e32 v5, v228, v229
	v_add_f32_e32 v4, v4, v5
	v_fmamk_f32 v4, v4, 0x3a800000, v212
	v_rsq_f32_e32 v6, v4
	s_add_u32 s12, s12, 0x2000
	s_addc_u32 s13, s13, 0
	v_pk_fma_f32 v[38:39], v[38:39], v[6:7], v[152:153] op_sel_hi:[1,0,1]
	v_pk_fma_f32 v[36:37], v[36:37], v[6:7], v[150:151] op_sel_hi:[1,0,1]
	v_pk_fma_f32 v[34:35], v[34:35], v[6:7], v[148:149] op_sel_hi:[1,0,1]
	v_pk_fma_f32 v[32:33], v[32:33], v[6:7], v[146:147] op_sel_hi:[1,0,1]
	v_pk_fma_f32 v[30:31], v[30:31], v[6:7], v[144:145] op_sel_hi:[1,0,1]
	v_pk_fma_f32 v[28:29], v[28:29], v[6:7], v[142:143] op_sel_hi:[1,0,1]
	v_pk_fma_f32 v[26:27], v[26:27], v[6:7], v[140:141] op_sel_hi:[1,0,1]
	v_pk_fma_f32 v[24:25], v[24:25], v[6:7], v[138:139] op_sel_hi:[1,0,1]
	s_add_u32 s18, s18, 0x4000
	s_addc_u32 s19, s19, 0
	global_store_dwordx4 v3, v[36:39], s[18:19]
	global_store_dwordx4 v3, v[32:35], s[18:19] offset:16
	global_store_dwordx4 v3, v[28:31], s[18:19] offset:128
	global_store_dwordx4 v3, v[24:27], s[18:19] offset:144
	v_cvt_pk_bf16_f32 v234, v36, v37
	v_cvt_pk_bf16_f32 v235, v38, v39
	v_cvt_pk_bf16_f32 v236, v32, v33
	v_cvt_pk_bf16_f32 v237, v34, v35
	v_cvt_pk_bf16_f32 v238, v28, v29
	v_cvt_pk_bf16_f32 v239, v30, v31
	v_cvt_pk_bf16_f32 v240, v24, v25
	v_cvt_pk_bf16_f32 v241, v26, v27
	s_mov_b64 vcc, s[6:7]
	v_cndmask_b32_dpp v36, v238, v234, vcc row_ror:8 row_mask:0xf bank_mask:0xf
	v_cndmask_b32_dpp v37, v239, v235, vcc row_ror:8 row_mask:0xf bank_mask:0xf
	v_cndmask_b32_dpp v38, v240, v236, vcc row_ror:8 row_mask:0xf bank_mask:0xf
	v_cndmask_b32_dpp v39, v241, v237, vcc row_ror:8 row_mask:0xf bank_mask:0xf
	s_not_b64 vcc, s[6:7]
	v_cndmask_b32_dpp v32, v234, v238, vcc row_ror:8 row_mask:0xf bank_mask:0xf
	v_cndmask_b32_dpp v33, v235, v239, vcc row_ror:8 row_mask:0xf bank_mask:0xf
	v_cndmask_b32_dpp v34, v236, v240, vcc row_ror:8 row_mask:0xf bank_mask:0xf
	v_cndmask_b32_dpp v35, v237, v241, vcc row_ror:8 row_mask:0xf bank_mask:0xf
	global_store_dwordx4 v246, v[36:39], s[12:13]
	global_store_dwordx4 v247, v[32:35], s[12:13]
	v_add_f32_e32 v4, v230, v231
	v_add_f32_e32 v5, v232, v233
	v_add_f32_e32 v4, v4, v5
	v_fmamk_f32 v4, v4, 0x3a800000, v212
	v_rsq_f32_e32 v6, v4
	s_add_u32 s12, s12, 0x2000
	s_addc_u32 s13, s13, 0
	v_pk_fma_f32 v[22:23], v[22:23], v[6:7], v[152:153] op_sel_hi:[1,0,1]
	v_pk_fma_f32 v[20:21], v[20:21], v[6:7], v[150:151] op_sel_hi:[1,0,1]
	v_pk_fma_f32 v[18:19], v[18:19], v[6:7], v[148:149] op_sel_hi:[1,0,1]
	v_pk_fma_f32 v[16:17], v[16:17], v[6:7], v[146:147] op_sel_hi:[1,0,1]
	v_pk_fma_f32 v[14:15], v[14:15], v[6:7], v[144:145] op_sel_hi:[1,0,1]
	v_pk_fma_f32 v[12:13], v[12:13], v[6:7], v[142:143] op_sel_hi:[1,0,1]
	v_pk_fma_f32 v[10:11], v[10:11], v[6:7], v[140:141] op_sel_hi:[1,0,1]
	v_pk_fma_f32 v[8:9], v[8:9], v[6:7], v[138:139] op_sel_hi:[1,0,1]
	s_add_u32 s18, s18, 0x4000
	s_addc_u32 s19, s19, 0
	global_store_dwordx4 v3, v[20:23], s[18:19]
	global_store_dwordx4 v3, v[16:19], s[18:19] offset:16
	global_store_dwordx4 v3, v[12:15], s[18:19] offset:128
	global_store_dwordx4 v3, v[8:11], s[18:19] offset:144
	v_cvt_pk_bf16_f32 v234, v20, v21
	v_cvt_pk_bf16_f32 v235, v22, v23
	v_cvt_pk_bf16_f32 v236, v16, v17
	v_cvt_pk_bf16_f32 v237, v18, v19
	v_cvt_pk_bf16_f32 v238, v12, v13
	v_cvt_pk_bf16_f32 v239, v14, v15
	v_cvt_pk_bf16_f32 v240, v8, v9
	v_cvt_pk_bf16_f32 v241, v10, v11
	s_mov_b64 vcc, s[6:7]
	v_cndmask_b32_dpp v20, v238, v234, vcc row_ror:8 row_mask:0xf bank_mask:0xf
	v_cndmask_b32_dpp v21, v239, v235, vcc row_ror:8 row_mask:0xf bank_mask:0xf
	v_cndmask_b32_dpp v22, v240, v236, vcc row_ror:8 row_mask:0xf bank_mask:0xf
	v_cndmask_b32_dpp v23, v241, v237, vcc row_ror:8 row_mask:0xf bank_mask:0xf
	s_not_b64 vcc, s[6:7]
	v_cndmask_b32_dpp v16, v234, v238, vcc row_ror:8 row_mask:0xf bank_mask:0xf
	v_cndmask_b32_dpp v17, v235, v239, vcc row_ror:8 row_mask:0xf bank_mask:0xf
	v_cndmask_b32_dpp v18, v236, v240, vcc row_ror:8 row_mask:0xf bank_mask:0xf
	v_cndmask_b32_dpp v19, v237, v241, vcc row_ror:8 row_mask:0xf bank_mask:0xf
	global_store_dwordx4 v246, v[20:23], s[12:13]
	global_store_dwordx4 v247, v[16:19], s[12:13]
	s_branch .LBB0_1422
